# split-K partials stored with agent-scope write-through stores, no L2 write-back before the flag
# speedup vs baseline: 1.0436x; 1.0044x over previous
; template <class Epi, class Sched, bool ALIGN_EPI = false, bool SP2 = false>
; __device__ __forceinline__ void gemm_phase(PG8_LAS unsigned char* lds, const Gemm g, const Sched& S, const Epi& E) {
;     ...
;         if constexpr (!Epi::AFTER_DRAIN) { E(acc, cur, wr, wc, fr, fq); S.done(cur); }
.LBB0_452:
	s_cmp_eq_u32 s101, 0
	s_cbranch_scc1 .Lsk_epi_normal
	v_readlane_b32 s6, v255, 49
	v_readlane_b32 s84, v255, 37
	v_readlane_b32 s85, v255, 38
	v_readlane_b32 s86, v255, 29
	v_readlane_b32 s87, v255, 30
	s_bfe_u32 s7, s101, 0x50008
	s_and_b32 s22, s101, 3
	v_and_b32_e32 v186, 63, v194
	v_lshlrev_b32_e32 v186, 4, v186
	s_lshl_b32 s23, s7, 8
	s_movk_i32 s2, 0x4000
	s_cmp_eq_u32 s77, 3
	s_cselect_b32 s2, 0x2000, s2
	s_add_i32 s23, s23, s2
	s_add_u32 s86, s86, s23
	s_addc_u32 s87, s87, 0
	s_lshl_b32 s6, s6, 15
	s_lshl_b32 s23, s7, 20
	s_add_i32 s23, s23, s6
	s_add_u32 s82, s84, s23
	s_addc_u32 s83, s85, 0
	s_lshl_b32 s23, s22, 18
	s_add_u32 s84, s82, s23
	s_addc_u32 s85, s83, 0
	s_cmp_eq_u32 s22, 2
	s_cbranch_scc1 .Lsk_st_lo
	s_cmp_eq_u32 s22, 3
	s_cbranch_scc1 .Lsk_st_hi
	global_store_dwordx4 v186, v[0:3], s[84:85] sc1
	global_store_dwordx4 v186, v[4:7], s[84:85] offset:1024 sc1
	global_store_dwordx4 v186, v[8:11], s[84:85] offset:2048 sc1
	global_store_dwordx4 v186, v[12:15], s[84:85] offset:3072 sc1
	s_add_u32 s84, s84, 0x1000
	s_addc_u32 s85, s85, 0
	global_store_dwordx4 v186, v[16:19], s[84:85] sc1
	global_store_dwordx4 v186, v[20:23], s[84:85] offset:1024 sc1
	global_store_dwordx4 v186, v[24:27], s[84:85] offset:2048 sc1
	global_store_dwordx4 v186, v[28:31], s[84:85] offset:3072 sc1
	s_add_u32 s84, s84, 0x1000
	s_addc_u32 s85, s85, 0
	global_store_dwordx4 v186, v[32:35], s[84:85] sc1
	global_store_dwordx4 v186, v[36:39], s[84:85] offset:1024 sc1
	global_store_dwordx4 v186, v[40:43], s[84:85] offset:2048 sc1
	global_store_dwordx4 v186, v[44:47], s[84:85] offset:3072 sc1
	s_add_u32 s84, s84, 0x1000
	s_addc_u32 s85, s85, 0
	global_store_dwordx4 v186, v[48:51], s[84:85] sc1
	global_store_dwordx4 v186, v[52:55], s[84:85] offset:1024 sc1
	global_store_dwordx4 v186, v[56:59], s[84:85] offset:2048 sc1
	global_store_dwordx4 v186, v[60:63], s[84:85] offset:3072 sc1
	s_add_u32 s84, s84, 0x1000
	s_addc_u32 s85, s85, 0
	global_store_dwordx4 v186, v[64:67], s[84:85] sc1
	global_store_dwordx4 v186, v[68:71], s[84:85] offset:1024 sc1
	global_store_dwordx4 v186, v[72:75], s[84:85] offset:2048 sc1
	global_store_dwordx4 v186, v[76:79], s[84:85] offset:3072 sc1
	s_add_u32 s84, s84, 0x1000
	s_addc_u32 s85, s85, 0
	global_store_dwordx4 v186, v[80:83], s[84:85] sc1
	global_store_dwordx4 v186, v[84:87], s[84:85] offset:1024 sc1
	global_store_dwordx4 v186, v[88:91], s[84:85] offset:2048 sc1
	global_store_dwordx4 v186, v[92:95], s[84:85] offset:3072 sc1
	s_add_u32 s84, s84, 0x1000
	s_addc_u32 s85, s85, 0
	global_store_dwordx4 v186, v[96:99], s[84:85] sc1
	global_store_dwordx4 v186, v[100:103], s[84:85] offset:1024 sc1
	global_store_dwordx4 v186, v[104:107], s[84:85] offset:2048 sc1
	global_store_dwordx4 v186, v[108:111], s[84:85] offset:3072 sc1
	s_add_u32 s84, s84, 0x1000
	s_addc_u32 s85, s85, 0
	global_store_dwordx4 v186, v[112:115], s[84:85] sc1
	global_store_dwordx4 v186, v[116:119], s[84:85] offset:1024 sc1
	global_store_dwordx4 v186, v[120:123], s[84:85] offset:2048 sc1
	global_store_dwordx4 v186, v[124:127], s[84:85] offset:3072 sc1
	s_branch .Lsk_publish
.Lsk_st_lo:
	global_store_dwordx4 v186, v[0:3], s[84:85] sc1
	global_store_dwordx4 v186, v[4:7], s[84:85] offset:1024 sc1
	global_store_dwordx4 v186, v[8:11], s[84:85] offset:2048 sc1
	global_store_dwordx4 v186, v[12:15], s[84:85] offset:3072 sc1
	s_add_u32 s84, s84, 0x1000
	s_addc_u32 s85, s85, 0
	global_store_dwordx4 v186, v[16:19], s[84:85] sc1
	global_store_dwordx4 v186, v[20:23], s[84:85] offset:1024 sc1
	global_store_dwordx4 v186, v[24:27], s[84:85] offset:2048 sc1
	global_store_dwordx4 v186, v[28:31], s[84:85] offset:3072 sc1
	s_add_u32 s84, s84, 0x1000
	s_addc_u32 s85, s85, 0
	global_store_dwordx4 v186, v[32:35], s[84:85] sc1
	global_store_dwordx4 v186, v[36:39], s[84:85] offset:1024 sc1
	global_store_dwordx4 v186, v[40:43], s[84:85] offset:2048 sc1
	global_store_dwordx4 v186, v[44:47], s[84:85] offset:3072 sc1
	s_add_u32 s84, s84, 0x1000
	s_addc_u32 s85, s85, 0
	global_store_dwordx4 v186, v[48:51], s[84:85] sc1
	global_store_dwordx4 v186, v[52:55], s[84:85] offset:1024 sc1
	global_store_dwordx4 v186, v[56:59], s[84:85] offset:2048 sc1
	global_store_dwordx4 v186, v[60:63], s[84:85] offset:3072 sc1
	s_branch .Lsk_publish
.Lsk_st_hi:
	s_add_u32 s84, s84, 0x4000
	s_addc_u32 s85, s85, 0
	global_store_dwordx4 v186, v[64:67], s[84:85] sc1
	global_store_dwordx4 v186, v[68:71], s[84:85] offset:1024 sc1
	global_store_dwordx4 v186, v[72:75], s[84:85] offset:2048 sc1
	global_store_dwordx4 v186, v[76:79], s[84:85] offset:3072 sc1
	s_add_u32 s84, s84, 0x1000
	s_addc_u32 s85, s85, 0
	global_store_dwordx4 v186, v[80:83], s[84:85] sc1
	global_store_dwordx4 v186, v[84:87], s[84:85] offset:1024 sc1
	global_store_dwordx4 v186, v[88:91], s[84:85] offset:2048 sc1
	global_store_dwordx4 v186, v[92:95], s[84:85] offset:3072 sc1
	s_add_u32 s84, s84, 0x1000
	s_addc_u32 s85, s85, 0
	global_store_dwordx4 v186, v[96:99], s[84:85] sc1
	global_store_dwordx4 v186, v[100:103], s[84:85] offset:1024 sc1
	global_store_dwordx4 v186, v[104:107], s[84:85] offset:2048 sc1
	global_store_dwordx4 v186, v[108:111], s[84:85] offset:3072 sc1
	s_add_u32 s84, s84, 0x1000
	s_addc_u32 s85, s85, 0
	global_store_dwordx4 v186, v[112:115], s[84:85] sc1
	global_store_dwordx4 v186, v[116:119], s[84:85] offset:1024 sc1
	global_store_dwordx4 v186, v[120:123], s[84:85] offset:2048 sc1
	global_store_dwordx4 v186, v[124:127], s[84:85] offset:3072 sc1
.Lsk_publish:
	s_waitcnt vmcnt(0)
	s_barrier
	s_cmp_lg_u32 s6, 0
	s_cbranch_scc1 .Lsk_pub_done
	s_mov_b64 s[84:85], exec
	s_mov_b64 exec, 1
	global_atomic_add v161, v196, s[86:87]
	s_mov_b64 exec, s[84:85]
	s_waitcnt vmcnt(0)

; template <class Epi, class Sched, bool ALIGN_EPI = false, bool SP2 = false>
; __device__ __forceinline__ void gemm_phase(PG8_LAS unsigned char* lds, const Gemm g, const Sched& S, const Epi& E) {
;     ...
;         if constexpr (!Epi::AFTER_DRAIN) { E(acc, cur, wr, wc, fr, fq); S.done(cur); }
.Lsk_ready:
	buffer_inv sc1
	s_waitcnt vmcnt(0)
	s_cmp_eq_u32 s22, 3
	s_cbranch_scc1 .Lsk_rd_hi
	s_add_u32 s84, s82, 0x4000
	s_addc_u32 s85, s83, 0
	global_load_dwordx4 v[128:131], v186, s[84:85] sc1
	global_load_dwordx4 v[132:135], v186, s[84:85] offset:1024 sc1
	global_load_dwordx4 v[136:139], v186, s[84:85] offset:2048 sc1
	global_load_dwordx4 v[140:143], v186, s[84:85] offset:3072 sc1
	s_add_u32 s84, s84, 0x1000
	s_addc_u32 s85, s85, 0
	global_load_dwordx4 v[144:147], v186, s[84:85] sc1
	global_load_dwordx4 v[148:151], v186, s[84:85] offset:1024 sc1
	global_load_dwordx4 v[152:155], v186, s[84:85] offset:2048 sc1
	global_load_dwordx4 v[156:159], v186, s[84:85] offset:3072 sc1
	s_add_u32 s84, s84, 0x1000
	s_addc_u32 s85, s85, 0
	global_load_dwordx4 v[212:215], v186, s[84:85] sc1
	global_load_dwordx4 v[216:219], v186, s[84:85] offset:1024 sc1
	global_load_dwordx4 v[220:223], v186, s[84:85] offset:2048 sc1
	global_load_dwordx4 v[224:227], v186, s[84:85] offset:3072 sc1
	s_add_u32 s84, s84, 0x1000
	s_addc_u32 s85, s85, 0
	global_load_dwordx4 v[228:231], v186, s[84:85] sc1
	global_load_dwordx4 v[232:235], v186, s[84:85] offset:1024 sc1
	global_load_dwordx4 v[188:191], v186, s[84:85] offset:2048 sc1
	global_load_dwordx4 v[236:239], v186, s[84:85] offset:3072 sc1
	s_waitcnt vmcnt(15)
	v_pk_add_f32 v[64:65], v[64:65], v[128:129]
	v_pk_add_f32 v[66:67], v[66:67], v[130:131]
	s_add_u32 s84, s84, 0x3d000
	s_addc_u32 s85, s85, 0
	global_load_dwordx4 v[128:131], v186, s[84:85] sc1
	s_waitcnt vmcnt(15)
	v_pk_add_f32 v[68:69], v[68:69], v[132:133]
	v_pk_add_f32 v[70:71], v[70:71], v[134:135]
	global_load_dwordx4 v[132:135], v186, s[84:85] offset:1024 sc1
	s_waitcnt vmcnt(15)
	v_pk_add_f32 v[72:73], v[72:73], v[136:137]
	v_pk_add_f32 v[74:75], v[74:75], v[138:139]
	global_load_dwordx4 v[136:139], v186, s[84:85] offset:2048 sc1
	s_waitcnt vmcnt(15)
	v_pk_add_f32 v[76:77], v[76:77], v[140:141]
	v_pk_add_f32 v[78:79], v[78:79], v[142:143]
	global_load_dwordx4 v[140:143], v186, s[84:85] offset:3072 sc1
	s_waitcnt vmcnt(15)
	v_pk_add_f32 v[80:81], v[80:81], v[144:145]
	v_pk_add_f32 v[82:83], v[82:83], v[146:147]
	s_add_u32 s84, s84, 0x1000
	s_addc_u32 s85, s85, 0
	global_load_dwordx4 v[144:147], v186, s[84:85] sc1
	s_waitcnt vmcnt(15)
	v_pk_add_f32 v[84:85], v[84:85], v[148:149]
	v_pk_add_f32 v[86:87], v[86:87], v[150:151]
	global_load_dwordx4 v[148:151], v186, s[84:85] offset:1024 sc1
	s_waitcnt vmcnt(15)
	v_pk_add_f32 v[88:89], v[88:89], v[152:153]
	v_pk_add_f32 v[90:91], v[90:91], v[154:155]
	global_load_dwordx4 v[152:155], v186, s[84:85] offset:2048 sc1
	s_waitcnt vmcnt(15)
	v_pk_add_f32 v[92:93], v[92:93], v[156:157]
	v_pk_add_f32 v[94:95], v[94:95], v[158:159]
	global_load_dwordx4 v[156:159], v186, s[84:85] offset:3072 sc1
	s_waitcnt vmcnt(15)
	v_pk_add_f32 v[96:97], v[96:97], v[212:213]
	v_pk_add_f32 v[98:99], v[98:99], v[214:215]
	s_add_u32 s84, s84, 0x1000
	s_addc_u32 s85, s85, 0
	global_load_dwordx4 v[212:215], v186, s[84:85] sc1
	s_waitcnt vmcnt(15)
	v_pk_add_f32 v[100:101], v[100:101], v[216:217]
	v_pk_add_f32 v[102:103], v[102:103], v[218:219]
	global_load_dwordx4 v[216:219], v186, s[84:85] offset:1024 sc1
	s_waitcnt vmcnt(15)
	v_pk_add_f32 v[104:105], v[104:105], v[220:221]
	v_pk_add_f32 v[106:107], v[106:107], v[222:223]
	global_load_dwordx4 v[220:223], v186, s[84:85] offset:2048 sc1
	s_waitcnt vmcnt(15)
	v_pk_add_f32 v[108:109], v[108:109], v[224:225]
	v_pk_add_f32 v[110:111], v[110:111], v[226:227]
	global_load_dwordx4 v[224:227], v186, s[84:85] offset:3072 sc1
	s_waitcnt vmcnt(15)
	v_pk_add_f32 v[112:113], v[112:113], v[228:229]
	v_pk_add_f32 v[114:115], v[114:115], v[230:231]
	s_add_u32 s84, s84, 0x1000
	s_addc_u32 s85, s85, 0
	global_load_dwordx4 v[228:231], v186, s[84:85] sc1
	s_waitcnt vmcnt(15)
	v_pk_add_f32 v[116:117], v[116:117], v[232:233]
	v_pk_add_f32 v[118:119], v[118:119], v[234:235]
	global_load_dwordx4 v[232:235], v186, s[84:85] offset:1024 sc1
	s_waitcnt vmcnt(15)
	v_pk_add_f32 v[120:121], v[120:121], v[188:189]
	v_pk_add_f32 v[122:123], v[122:123], v[190:191]
	global_load_dwordx4 v[188:191], v186, s[84:85] offset:2048 sc1
	s_waitcnt vmcnt(15)
	v_pk_add_f32 v[124:125], v[124:125], v[236:237]
	v_pk_add_f32 v[126:127], v[126:127], v[238:239]
	global_load_dwordx4 v[236:239], v186, s[84:85] offset:3072 sc1
	s_waitcnt vmcnt(15)
	v_pk_add_f32 v[64:65], v[64:65], v[128:129]
	v_pk_add_f32 v[66:67], v[66:67], v[130:131]
	s_add_u32 s84, s84, 0x7d000
	s_addc_u32 s85, s85, 0
	global_load_dwordx4 v[128:131], v186, s[84:85] sc1
	s_waitcnt vmcnt(15)
	v_pk_add_f32 v[68:69], v[68:69], v[132:133]
	v_pk_add_f32 v[70:71], v[70:71], v[134:135]
	global_load_dwordx4 v[132:135], v186, s[84:85] offset:1024 sc1
	s_waitcnt vmcnt(15)
	v_pk_add_f32 v[72:73], v[72:73], v[136:137]
	v_pk_add_f32 v[74:75], v[74:75], v[138:139]
	global_load_dwordx4 v[136:139], v186, s[84:85] offset:2048 sc1
	s_waitcnt vmcnt(15)
	v_pk_add_f32 v[76:77], v[76:77], v[140:141]
	v_pk_add_f32 v[78:79], v[78:79], v[142:143]
	global_load_dwordx4 v[140:143], v186, s[84:85] offset:3072 sc1
	s_waitcnt vmcnt(15)
	v_pk_add_f32 v[80:81], v[80:81], v[144:145]
	v_pk_add_f32 v[82:83], v[82:83], v[146:147]
	s_add_u32 s84, s84, 0x1000
	s_addc_u32 s85, s85, 0
	global_load_dwordx4 v[144:147], v186, s[84:85] sc1
	s_waitcnt vmcnt(15)
	v_pk_add_f32 v[84:85], v[84:85], v[148:149]
	v_pk_add_f32 v[86:87], v[86:87], v[150:151]
	global_load_dwordx4 v[148:151], v186, s[84:85] offset:1024 sc1
	s_waitcnt vmcnt(15)
	v_pk_add_f32 v[88:89], v[88:89], v[152:153]
	v_pk_add_f32 v[90:91], v[90:91], v[154:155]
	global_load_dwordx4 v[152:155], v186, s[84:85] offset:2048 sc1
	s_waitcnt vmcnt(15)
; template <class Epi, class Sched, bool ALIGN_EPI = false, bool SP2 = false>
; __device__ __forceinline__ void gemm_phase(PG8_LAS unsigned char* lds, const Gemm g, const Sched& S, const Epi& E) {
;     ...
;         if constexpr (!Epi::AFTER_DRAIN) { E(acc, cur, wr, wc, fr, fq); S.done(cur); }
	v_pk_add_f32 v[92:93], v[92:93], v[156:157]
	v_pk_add_f32 v[94:95], v[94:95], v[158:159]
	global_load_dwordx4 v[156:159], v186, s[84:85] offset:3072 sc1
	s_waitcnt vmcnt(15)
	v_pk_add_f32 v[96:97], v[96:97], v[212:213]
	v_pk_add_f32 v[98:99], v[98:99], v[214:215]
	s_add_u32 s84, s84, 0x1000
	s_addc_u32 s85, s85, 0
	global_load_dwordx4 v[212:215], v186, s[84:85] sc1
	s_waitcnt vmcnt(15)
	v_pk_add_f32 v[100:101], v[100:101], v[216:217]
	v_pk_add_f32 v[102:103], v[102:103], v[218:219]
	global_load_dwordx4 v[216:219], v186, s[84:85] offset:1024 sc1
	s_waitcnt vmcnt(15)
	v_pk_add_f32 v[104:105], v[104:105], v[220:221]
	v_pk_add_f32 v[106:107], v[106:107], v[222:223]
	global_load_dwordx4 v[220:223], v186, s[84:85] offset:2048 sc1
	s_waitcnt vmcnt(15)
	v_pk_add_f32 v[108:109], v[108:109], v[224:225]
	v_pk_add_f32 v[110:111], v[110:111], v[226:227]
	global_load_dwordx4 v[224:227], v186, s[84:85] offset:3072 sc1
	s_waitcnt vmcnt(15)
	v_pk_add_f32 v[112:113], v[112:113], v[228:229]
	v_pk_add_f32 v[114:115], v[114:115], v[230:231]
	s_add_u32 s84, s84, 0x1000
	s_addc_u32 s85, s85, 0
	global_load_dwordx4 v[228:231], v186, s[84:85] sc1
	s_waitcnt vmcnt(15)
	v_pk_add_f32 v[116:117], v[116:117], v[232:233]
	v_pk_add_f32 v[118:119], v[118:119], v[234:235]
	global_load_dwordx4 v[232:235], v186, s[84:85] offset:1024 sc1
	s_waitcnt vmcnt(15)
	v_pk_add_f32 v[120:121], v[120:121], v[188:189]
	v_pk_add_f32 v[122:123], v[122:123], v[190:191]
	global_load_dwordx4 v[188:191], v186, s[84:85] offset:2048 sc1
	s_waitcnt vmcnt(15)
	v_pk_add_f32 v[124:125], v[124:125], v[236:237]
	v_pk_add_f32 v[126:127], v[126:127], v[238:239]
	global_load_dwordx4 v[236:239], v186, s[84:85] offset:3072 sc1
	s_waitcnt vmcnt(15)
	v_pk_add_f32 v[64:65], v[64:65], v[128:129]
	v_pk_add_f32 v[66:67], v[66:67], v[130:131]
	s_waitcnt vmcnt(14)
	v_pk_add_f32 v[68:69], v[68:69], v[132:133]
	v_pk_add_f32 v[70:71], v[70:71], v[134:135]
	s_waitcnt vmcnt(13)
	v_pk_add_f32 v[72:73], v[72:73], v[136:137]
	v_pk_add_f32 v[74:75], v[74:75], v[138:139]
	s_waitcnt vmcnt(12)
	v_pk_add_f32 v[76:77], v[76:77], v[140:141]
	v_pk_add_f32 v[78:79], v[78:79], v[142:143]
	s_waitcnt vmcnt(11)
	v_pk_add_f32 v[80:81], v[80:81], v[144:145]
	v_pk_add_f32 v[82:83], v[82:83], v[146:147]
	s_waitcnt vmcnt(10)
	v_pk_add_f32 v[84:85], v[84:85], v[148:149]
	v_pk_add_f32 v[86:87], v[86:87], v[150:151]
	s_waitcnt vmcnt(9)
	v_pk_add_f32 v[88:89], v[88:89], v[152:153]
	v_pk_add_f32 v[90:91], v[90:91], v[154:155]
	s_waitcnt vmcnt(8)
	v_pk_add_f32 v[92:93], v[92:93], v[156:157]
	v_pk_add_f32 v[94:95], v[94:95], v[158:159]
	s_waitcnt vmcnt(7)
	v_pk_add_f32 v[96:97], v[96:97], v[212:213]
	v_pk_add_f32 v[98:99], v[98:99], v[214:215]
	s_waitcnt vmcnt(6)
	v_pk_add_f32 v[100:101], v[100:101], v[216:217]
	v_pk_add_f32 v[102:103], v[102:103], v[218:219]
	s_waitcnt vmcnt(5)
	v_pk_add_f32 v[104:105], v[104:105], v[220:221]
	v_pk_add_f32 v[106:107], v[106:107], v[222:223]
	s_waitcnt vmcnt(4)
	v_pk_add_f32 v[108:109], v[108:109], v[224:225]
	v_pk_add_f32 v[110:111], v[110:111], v[226:227]
	s_waitcnt vmcnt(3)
	v_pk_add_f32 v[112:113], v[112:113], v[228:229]
	v_pk_add_f32 v[114:115], v[114:115], v[230:231]
	s_waitcnt vmcnt(2)
	v_pk_add_f32 v[116:117], v[116:117], v[232:233]
	v_pk_add_f32 v[118:119], v[118:119], v[234:235]
	s_waitcnt vmcnt(1)
	v_pk_add_f32 v[120:121], v[120:121], v[188:189]
	v_pk_add_f32 v[122:123], v[122:123], v[190:191]
	s_waitcnt vmcnt(0)
	v_pk_add_f32 v[124:125], v[124:125], v[236:237]
	v_pk_add_f32 v[126:127], v[126:127], v[238:239]
	s_branch .Lsk_epi_normal
.Lsk_rd_hi:
	s_add_u32 s84, s82, 0
	s_addc_u32 s85, s83, 0
	global_load_dwordx4 v[128:131], v186, s[84:85] sc1
	global_load_dwordx4 v[132:135], v186, s[84:85] offset:1024 sc1
	global_load_dwordx4 v[136:139], v186, s[84:85] offset:2048 sc1
	global_load_dwordx4 v[140:143], v186, s[84:85] offset:3072 sc1
	s_add_u32 s84, s84, 0x1000
	s_addc_u32 s85, s85, 0
	global_load_dwordx4 v[144:147], v186, s[84:85] sc1
	global_load_dwordx4 v[148:151], v186, s[84:85] offset:1024 sc1
	global_load_dwordx4 v[152:155], v186, s[84:85] offset:2048 sc1
	global_load_dwordx4 v[156:159], v186, s[84:85] offset:3072 sc1
	s_add_u32 s84, s84, 0x1000
	s_addc_u32 s85, s85, 0
	global_load_dwordx4 v[212:215], v186, s[84:85] sc1
	global_load_dwordx4 v[216:219], v186, s[84:85] offset:1024 sc1
	global_load_dwordx4 v[220:223], v186, s[84:85] offset:2048 sc1
	global_load_dwordx4 v[224:227], v186, s[84:85] offset:3072 sc1
	s_add_u32 s84, s84, 0x1000
	s_addc_u32 s85, s85, 0
	global_load_dwordx4 v[228:231], v186, s[84:85] sc1
	global_load_dwordx4 v[232:235], v186, s[84:85] offset:1024 sc1
	global_load_dwordx4 v[188:191], v186, s[84:85] offset:2048 sc1
	global_load_dwordx4 v[236:239], v186, s[84:85] offset:3072 sc1
	s_waitcnt vmcnt(15)
	v_pk_add_f32 v[0:1], v[0:1], v[128:129]
	v_pk_add_f32 v[2:3], v[2:3], v[130:131]
	s_add_u32 s84, s84, 0x3d000
	s_addc_u32 s85, s85, 0
	global_load_dwordx4 v[128:131], v186, s[84:85] sc1
	s_waitcnt vmcnt(15)
	v_pk_add_f32 v[4:5], v[4:5], v[132:133]
	v_pk_add_f32 v[6:7], v[6:7], v[134:135]
	global_load_dwordx4 v[132:135], v186, s[84:85] offset:1024 sc1
	s_waitcnt vmcnt(15)
	v_pk_add_f32 v[8:9], v[8:9], v[136:137]
	v_pk_add_f32 v[10:11], v[10:11], v[138:139]
	global_load_dwordx4 v[136:139], v186, s[84:85] offset:2048 sc1
	s_waitcnt vmcnt(15)
	v_pk_add_f32 v[12:13], v[12:13], v[140:141]
	v_pk_add_f32 v[14:15], v[14:15], v[142:143]
	global_load_dwordx4 v[140:143], v186, s[84:85] offset:3072 sc1
	s_waitcnt vmcnt(15)
	v_pk_add_f32 v[16:17], v[16:17], v[144:145]
	v_pk_add_f32 v[18:19], v[18:19], v[146:147]
	s_add_u32 s84, s84, 0x1000
	s_addc_u32 s85, s85, 0
	global_load_dwordx4 v[144:147], v186, s[84:85] sc1
	s_waitcnt vmcnt(15)
; template <class Epi, class Sched, bool ALIGN_EPI = false, bool SP2 = false>
; __device__ __forceinline__ void gemm_phase(PG8_LAS unsigned char* lds, const Gemm g, const Sched& S, const Epi& E) {
;     ...
;         if constexpr (!Epi::AFTER_DRAIN) { E(acc, cur, wr, wc, fr, fq); S.done(cur); }
	v_pk_add_f32 v[20:21], v[20:21], v[148:149]
	v_pk_add_f32 v[22:23], v[22:23], v[150:151]
	global_load_dwordx4 v[148:151], v186, s[84:85] offset:1024 sc1
	s_waitcnt vmcnt(15)
	v_pk_add_f32 v[24:25], v[24:25], v[152:153]
	v_pk_add_f32 v[26:27], v[26:27], v[154:155]
	global_load_dwordx4 v[152:155], v186, s[84:85] offset:2048 sc1
	s_waitcnt vmcnt(15)
	v_pk_add_f32 v[28:29], v[28:29], v[156:157]
	v_pk_add_f32 v[30:31], v[30:31], v[158:159]
	global_load_dwordx4 v[156:159], v186, s[84:85] offset:3072 sc1
	s_waitcnt vmcnt(15)
	v_pk_add_f32 v[32:33], v[32:33], v[212:213]
	v_pk_add_f32 v[34:35], v[34:35], v[214:215]
	s_add_u32 s84, s84, 0x1000
	s_addc_u32 s85, s85, 0
	global_load_dwordx4 v[212:215], v186, s[84:85] sc1
	s_waitcnt vmcnt(15)
	v_pk_add_f32 v[36:37], v[36:37], v[216:217]
	v_pk_add_f32 v[38:39], v[38:39], v[218:219]
	global_load_dwordx4 v[216:219], v186, s[84:85] offset:1024 sc1
	s_waitcnt vmcnt(15)
	v_pk_add_f32 v[40:41], v[40:41], v[220:221]
	v_pk_add_f32 v[42:43], v[42:43], v[222:223]
	global_load_dwordx4 v[220:223], v186, s[84:85] offset:2048 sc1
	s_waitcnt vmcnt(15)
	v_pk_add_f32 v[44:45], v[44:45], v[224:225]
	v_pk_add_f32 v[46:47], v[46:47], v[226:227]
	global_load_dwordx4 v[224:227], v186, s[84:85] offset:3072 sc1
	s_waitcnt vmcnt(15)
	v_pk_add_f32 v[48:49], v[48:49], v[228:229]
	v_pk_add_f32 v[50:51], v[50:51], v[230:231]
	s_add_u32 s84, s84, 0x1000
	s_addc_u32 s85, s85, 0
	global_load_dwordx4 v[228:231], v186, s[84:85] sc1
	s_waitcnt vmcnt(15)
	v_pk_add_f32 v[52:53], v[52:53], v[232:233]
	v_pk_add_f32 v[54:55], v[54:55], v[234:235]
	global_load_dwordx4 v[232:235], v186, s[84:85] offset:1024 sc1
	s_waitcnt vmcnt(15)
	v_pk_add_f32 v[56:57], v[56:57], v[188:189]
	v_pk_add_f32 v[58:59], v[58:59], v[190:191]
	global_load_dwordx4 v[188:191], v186, s[84:85] offset:2048 sc1
	s_waitcnt vmcnt(15)
	v_pk_add_f32 v[60:61], v[60:61], v[236:237]
	v_pk_add_f32 v[62:63], v[62:63], v[238:239]
	global_load_dwordx4 v[236:239], v186, s[84:85] offset:3072 sc1
	s_waitcnt vmcnt(15)
	v_pk_add_f32 v[0:1], v[0:1], v[128:129]
	v_pk_add_f32 v[2:3], v[2:3], v[130:131]
	s_add_u32 s84, s84, 0x3d000
	s_addc_u32 s85, s85, 0
	global_load_dwordx4 v[128:131], v186, s[84:85] sc1
	s_waitcnt vmcnt(15)
	v_pk_add_f32 v[4:5], v[4:5], v[132:133]
	v_pk_add_f32 v[6:7], v[6:7], v[134:135]
	global_load_dwordx4 v[132:135], v186, s[84:85] offset:1024 sc1
	s_waitcnt vmcnt(15)
	v_pk_add_f32 v[8:9], v[8:9], v[136:137]
	v_pk_add_f32 v[10:11], v[10:11], v[138:139]
	global_load_dwordx4 v[136:139], v186, s[84:85] offset:2048 sc1
	s_waitcnt vmcnt(15)
	v_pk_add_f32 v[12:13], v[12:13], v[140:141]
	v_pk_add_f32 v[14:15], v[14:15], v[142:143]
	global_load_dwordx4 v[140:143], v186, s[84:85] offset:3072 sc1
	s_waitcnt vmcnt(15)
	v_pk_add_f32 v[16:17], v[16:17], v[144:145]
	v_pk_add_f32 v[18:19], v[18:19], v[146:147]
	s_add_u32 s84, s84, 0x1000
	s_addc_u32 s85, s85, 0
	global_load_dwordx4 v[144:147], v186, s[84:85] sc1
	s_waitcnt vmcnt(15)
	v_pk_add_f32 v[20:21], v[20:21], v[148:149]
	v_pk_add_f32 v[22:23], v[22:23], v[150:151]
	global_load_dwordx4 v[148:151], v186, s[84:85] offset:1024 sc1
	s_waitcnt vmcnt(15)
	v_pk_add_f32 v[24:25], v[24:25], v[152:153]
	v_pk_add_f32 v[26:27], v[26:27], v[154:155]
	global_load_dwordx4 v[152:155], v186, s[84:85] offset:2048 sc1
	s_waitcnt vmcnt(15)
	v_pk_add_f32 v[28:29], v[28:29], v[156:157]
	v_pk_add_f32 v[30:31], v[30:31], v[158:159]
	global_load_dwordx4 v[156:159], v186, s[84:85] offset:3072 sc1
	s_waitcnt vmcnt(15)
; template <class Epi, class Sched, bool ALIGN_EPI = false, bool SP2 = false>
; __device__ __forceinline__ void gemm_phase(PG8_LAS unsigned char* lds, const Gemm g, const Sched& S, const Epi& E) {
;     ...
;         if constexpr (!Epi::AFTER_DRAIN) { E(acc, cur, wr, wc, fr, fq); S.done(cur); }
;     DI void operator()(const f32x4 (&acc)[2][2][4][2], const Unit& u, int wr, int wc, int fr, int fq) const {
;         asm volatile("" : "+v"(fr), "+v"(fq));
;         const int row0 = u.pm * 256 + wr * 64 + fr, col0 = u.pn * 256 + wc * 32 + 8 * fq;
	v_pk_add_f32 v[32:33], v[32:33], v[212:213]
	v_pk_add_f32 v[34:35], v[34:35], v[214:215]
	s_add_u32 s84, s84, 0x1000
	s_addc_u32 s85, s85, 0
	global_load_dwordx4 v[212:215], v186, s[84:85] sc1
	s_waitcnt vmcnt(15)
	v_pk_add_f32 v[36:37], v[36:37], v[216:217]
	v_pk_add_f32 v[38:39], v[38:39], v[218:219]
	global_load_dwordx4 v[216:219], v186, s[84:85] offset:1024 sc1
	s_waitcnt vmcnt(15)
	v_pk_add_f32 v[40:41], v[40:41], v[220:221]
	v_pk_add_f32 v[42:43], v[42:43], v[222:223]
	global_load_dwordx4 v[220:223], v186, s[84:85] offset:2048 sc1
	s_waitcnt vmcnt(15)
	v_pk_add_f32 v[44:45], v[44:45], v[224:225]
	v_pk_add_f32 v[46:47], v[46:47], v[226:227]
	global_load_dwordx4 v[224:227], v186, s[84:85] offset:3072 sc1
	s_waitcnt vmcnt(15)
	v_pk_add_f32 v[48:49], v[48:49], v[228:229]
	v_pk_add_f32 v[50:51], v[50:51], v[230:231]
	s_add_u32 s84, s84, 0x1000
	s_addc_u32 s85, s85, 0
	global_load_dwordx4 v[228:231], v186, s[84:85] sc1
	s_waitcnt vmcnt(15)
	v_pk_add_f32 v[52:53], v[52:53], v[232:233]
	v_pk_add_f32 v[54:55], v[54:55], v[234:235]
	global_load_dwordx4 v[232:235], v186, s[84:85] offset:1024 sc1
	s_waitcnt vmcnt(15)
	v_pk_add_f32 v[56:57], v[56:57], v[188:189]
	v_pk_add_f32 v[58:59], v[58:59], v[190:191]
	global_load_dwordx4 v[188:191], v186, s[84:85] offset:2048 sc1
	s_waitcnt vmcnt(15)
	v_pk_add_f32 v[60:61], v[60:61], v[236:237]
	v_pk_add_f32 v[62:63], v[62:63], v[238:239]
	global_load_dwordx4 v[236:239], v186, s[84:85] offset:3072 sc1
	s_waitcnt vmcnt(15)
	v_pk_add_f32 v[0:1], v[0:1], v[128:129]
	v_pk_add_f32 v[2:3], v[2:3], v[130:131]
	s_waitcnt vmcnt(14)
	v_pk_add_f32 v[4:5], v[4:5], v[132:133]
	v_pk_add_f32 v[6:7], v[6:7], v[134:135]
	s_waitcnt vmcnt(13)
	v_pk_add_f32 v[8:9], v[8:9], v[136:137]
	v_pk_add_f32 v[10:11], v[10:11], v[138:139]
	s_waitcnt vmcnt(12)
	v_pk_add_f32 v[12:13], v[12:13], v[140:141]
	v_pk_add_f32 v[14:15], v[14:15], v[142:143]
	s_waitcnt vmcnt(11)
	v_pk_add_f32 v[16:17], v[16:17], v[144:145]
	v_pk_add_f32 v[18:19], v[18:19], v[146:147]
	s_waitcnt vmcnt(10)
	v_pk_add_f32 v[20:21], v[20:21], v[148:149]
	v_pk_add_f32 v[22:23], v[22:23], v[150:151]
	s_waitcnt vmcnt(9)
	v_pk_add_f32 v[24:25], v[24:25], v[152:153]
	v_pk_add_f32 v[26:27], v[26:27], v[154:155]
	s_waitcnt vmcnt(8)
	v_pk_add_f32 v[28:29], v[28:29], v[156:157]
	v_pk_add_f32 v[30:31], v[30:31], v[158:159]
	s_waitcnt vmcnt(7)
	v_pk_add_f32 v[32:33], v[32:33], v[212:213]
	v_pk_add_f32 v[34:35], v[34:35], v[214:215]
	s_waitcnt vmcnt(6)
	v_pk_add_f32 v[36:37], v[36:37], v[216:217]
	v_pk_add_f32 v[38:39], v[38:39], v[218:219]
	s_waitcnt vmcnt(5)
	v_pk_add_f32 v[40:41], v[40:41], v[220:221]
	v_pk_add_f32 v[42:43], v[42:43], v[222:223]
	s_waitcnt vmcnt(4)
	v_pk_add_f32 v[44:45], v[44:45], v[224:225]
	v_pk_add_f32 v[46:47], v[46:47], v[226:227]
	s_waitcnt vmcnt(3)
	v_pk_add_f32 v[48:49], v[48:49], v[228:229]
	v_pk_add_f32 v[50:51], v[50:51], v[230:231]
	s_waitcnt vmcnt(2)
	v_pk_add_f32 v[52:53], v[52:53], v[232:233]
	v_pk_add_f32 v[54:55], v[54:55], v[234:235]
	s_waitcnt vmcnt(1)
	v_pk_add_f32 v[56:57], v[56:57], v[188:189]
	v_pk_add_f32 v[58:59], v[58:59], v[190:191]
	s_waitcnt vmcnt(0)
	v_pk_add_f32 v[60:61], v[60:61], v[236:237]
	v_pk_add_f32 v[62:63], v[62:63], v[238:239]
	s_lshl_b32 s42, s42, 8
	s_add_i32 s42, s42, s41
	s_lshl_b32 s6, s43, 8
	s_or_b32 s6, s6, s44
	v_lshl_add_u32 v186, v208, 3, s6
	v_readlane_b32 s6, v253, 22
	v_readlane_b32 s7, v253, 23
	v_ashrrev_i32_e32 v187, 31, v186
	v_add_u32_e32 v190, s42, v173
	v_cndmask_b32_e64 v136, 0, 1, s[8:9]
	v_lshl_add_u64 v[188:189], v[186:187], 1, s[6:7]
	v_cmp_ne_u32_e64 s[6:7], 1, v136
	s_branch .LBB0_548
